# v68 + transposer items (P0 and P1 loops): v_cvt_pk_bf16_f32 instead of the 6-instruction RNE bit-trick per packed pair (same rounding), s_nop pads after the 128-bit stores
# speedup vs baseline: 1.0027x; 1.0027x over previous
; #define LAS __attribute__((address_space(3)))
; #define LDS_WAIT() asm volatile("s_waitcnt lgkmcnt(0)" ::: "memory")
; __device__ __forceinline__ unsigned pk2(float lo, float hi) { return (unsigned)f2bf(lo) | ((unsigned)f2bf(hi) << 16); }
; __device__ __forceinline__ unsigned xb_add(unsigned* p, unsigned v) { return __hip_atomic_fetch_add(p, v, __ATOMIC_RELAXED, __HIP_MEMORY_SCOPE_AGENT); }
; __device__ __forceinline__ void p0_item_load(const P0Item& d, f32x4 (&v)[8], int lane) {
; #pragma unroll
;     for (int i = 0; i < 8; ++i) v[i] = __builtin_nontemporal_load((const f32x4*)(d.src + (size_t)(8 * i + (lane >> 3)) * d.N + 4 * (lane & 7)));
; }
; template <bool WT = false>
; __device__ __forceinline__ void p0_item_finish(const P0Item& d, const f32x4 (&v)[8], LAS float* scr, int lane) {
; #pragma unroll
;     for (int i = 0; i < 8; ++i) { LAS float* q = scr + (8 * i + (lane >> 3)) * 33 + 4 * (lane & 7); q[0] = v[i][0]; q[1] = v[i][1]; q[2] = v[i][2]; q[3] = v[i][3]; }
;     LDS_WAIT(); asm volatile("" ::: "memory");
;     const int c = lane & 7;
; #pragma unroll
;     for (int j = 0; j < 4; ++j) { const int n = (lane >> 3) + 8 * j; const LAS float* s = scr + (8 * c) * 33 + n;
;         v4u o; o.x = pk2(s[0 * 33], s[1 * 33]); o.y = pk2(s[2 * 33], s[3 * 33]); o.z = pk2(s[4 * 33], s[5 * 33]); o.w = pk2(s[6 * 33], s[7 * 33]);
;         if constexpr (WT) __builtin_amdgcn_raw_buffer_store_b128(o, __builtin_amdgcn_make_buffer_rsrc((void*)d.dst, 0, 0x7fffffff, 0x00020000), (int)(((size_t)n * d.ldt + 8 * c) * 2), 0, 16);
;         else *(v4u*)(d.dst + (size_t)n * d.ldt + 8 * c) = o; }
;     LDS_WAIT(); asm volatile("" ::: "memory");
; }
; __device__ __forceinline__ void tr_blocks(Frame& F, const Args& a, int T, int b_lo, int b_hi, bool tail) {
;     ...
;         db = p0_item_in(a, T, 8 * (b + 1) + w); p0_item_load(db, vb, F.lane);
;         p0_item_finish<true>(da, va, scr, F.lane);
;         if (b > b_lo) { asm volatile("s_waitcnt vmcnt(12)" ::: "memory"); __syncthreads(); if (F.tid == 0) (void)xb_add(blk + 16 * (b - 1), 1u); }
.LBB0_114:
	s_lshl_b64 s[4:5], s[28:29], 12
	s_add_u32 s4, s35, s4
	s_addc_u32 s5, s53, s5
	s_ashr_i32 s39, s38, 31
	v_lshl_add_u64 v[34:35], s[38:39], 2, v[68:69]
	v_lshl_add_u64 v[58:59], v[34:35], 0, v[66:67]
	v_add_co_u32_e32 v38, vcc, s0, v58
	v_add_u32_e32 v75, 0x420, v74
	s_nop 0
	v_addc_co_u32_e32 v39, vcc, 0, v59, vcc
	v_add_co_u32_e32 v42, vcc, s1, v58
	global_load_dwordx4 v[34:37], v[58:59], off nt
	s_nop 0
	global_load_dwordx4 v[38:41], v[38:39], off offset:1024 nt
	v_addc_co_u32_e32 v43, vcc, 0, v59, vcc
	v_add_co_u32_e32 v46, vcc, s8, v58
	v_add_u32_e32 v76, 0x428, v74
	s_nop 0
	v_addc_co_u32_e32 v47, vcc, 0, v59, vcc
	v_add_co_u32_e32 v50, vcc, s9, v58
	global_load_dwordx4 v[42:45], v[42:43], off offset:2048 nt
	s_nop 0
	global_load_dwordx4 v[46:49], v[46:47], off offset:3072 nt
	v_addc_co_u32_e32 v51, vcc, 0, v59, vcc
	v_add_co_u32_e32 v54, vcc, s10, v58
	v_add_u32_e32 v77, 0x840, v74
	s_nop 0
	v_addc_co_u32_e32 v55, vcc, 0, v59, vcc
	v_add_co_u32_e32 v60, vcc, s11, v58
	global_load_dwordx4 v[50:53], v[50:51], off nt
	s_nop 0
	global_load_dwordx4 v[54:57], v[54:55], off offset:1024 nt
	v_addc_co_u32_e32 v61, vcc, 0, v59, vcc
	v_add_co_u32_e32 v62, vcc, s33, v58
	v_add_u32_e32 v78, 0x848, v74
	s_nop 0
	v_addc_co_u32_e32 v63, vcc, 0, v59, vcc
	global_load_dwordx4 v[58:61], v[60:61], off offset:2048 nt
	s_nop 0
	global_load_dwordx4 v[62:65], v[62:63], off offset:3072 nt
	v_add_u32_e32 v79, 0xc60, v74
	v_add_u32_e32 v80, 0xc68, v74
	v_add_u32_e32 v81, 0x1080, v74
	v_add_u32_e32 v82, 0x1088, v74
	v_add_u32_e32 v83, 0x14a0, v74
	v_add_u32_e32 v84, 0x14a8, v74
	v_add_u32_e32 v85, 0x18c0, v74
	v_add_u32_e32 v86, 0x18c8, v74
	v_add_u32_e32 v87, 0x1ce0, v74
	v_add_u32_e32 v88, 0x1ce8, v74
	s_waitcnt vmcnt(15)
	ds_write2_b32 v74, v2, v3 offset1:1
	ds_write2_b32 v74, v4, v5 offset0:2 offset1:3
	s_waitcnt vmcnt(14)
	ds_write2_b32 v75, v6, v7 offset1:1
	ds_write2_b32 v76, v8, v9 offset1:1
	s_waitcnt vmcnt(13)
	ds_write2_b32 v77, v10, v11 offset1:1
	ds_write2_b32 v78, v12, v13 offset1:1
	s_waitcnt vmcnt(12)
	ds_write2_b32 v79, v14, v15 offset1:1
	ds_write2_b32 v80, v16, v17 offset1:1
	s_waitcnt vmcnt(11)
	ds_write2_b32 v81, v18, v19 offset1:1
	ds_write2_b32 v82, v20, v21 offset1:1
	s_waitcnt vmcnt(10)
	ds_write2_b32 v83, v22, v23 offset1:1
	ds_write2_b32 v84, v24, v25 offset1:1
	s_waitcnt vmcnt(9)
	ds_write2_b32 v85, v26, v27 offset1:1
	ds_write2_b32 v86, v28, v29 offset1:1
	s_waitcnt vmcnt(8)
	ds_write2_b32 v87, v30, v31 offset1:1
	ds_write2_b32 v88, v32, v33 offset1:1
	s_waitcnt lgkmcnt(0)
	ds_read2_b32 v[6:7], v1 offset1:8
	ds_read2_b32 v[8:9], v1 offset0:33 offset1:41
	ds_read2_b32 v[10:11], v1 offset0:66 offset1:74
	ds_read2_b32 v[12:13], v1 offset0:99 offset1:107
	ds_read2_b32 v[14:15], v1 offset0:132 offset1:140
	s_waitcnt lgkmcnt(4)
	s_waitcnt lgkmcnt(3)
	ds_read2_b32 v[16:17], v1 offset0:165 offset1:173
	v_cvt_pk_bf16_f32 v2, v6, v8
	s_waitcnt lgkmcnt(3)
	s_waitcnt lgkmcnt(2)
	ds_read2_b32 v[18:19], v1 offset0:198 offset1:206
	ds_read2_b32 v[20:21], v1 offset0:231 offset1:239
	v_cvt_pk_bf16_f32 v3, v10, v12
	s_waitcnt lgkmcnt(3)
	s_waitcnt lgkmcnt(2)
	v_cvt_pk_bf16_f32 v4, v14, v16
	s_waitcnt lgkmcnt(1)
	s_waitcnt lgkmcnt(0)
	s_and_b32 s5, s5, 0xffff
	v_cvt_pk_bf16_f32 v5, v18, v20
	buffer_store_dwordx4 v[2:5], v70, s[4:7], 0 offen sc1
	s_nop 1
	v_cvt_pk_bf16_f32 v2, v7, v9
	v_cvt_pk_bf16_f32 v3, v11, v13
	v_cvt_pk_bf16_f32 v4, v15, v17
	ds_read2_b32 v[6:7], v1 offset0:16 offset1:24
	v_cvt_pk_bf16_f32 v5, v19, v21
	ds_read2_b32 v[8:9], v1 offset0:49 offset1:57
	ds_read2_b32 v[10:11], v1 offset0:82 offset1:90
	ds_read2_b32 v[12:13], v1 offset0:115 offset1:123
	buffer_store_dwordx4 v[2:5], v71, s[4:7], 0 offen sc1
	s_nop 1
	ds_read2_b32 v[14:15], v1 offset0:148 offset1:156
	ds_read2_b32 v[16:17], v1 offset0:181 offset1:189
	s_waitcnt lgkmcnt(5)
	s_waitcnt lgkmcnt(4)
	v_cvt_pk_bf16_f32 v2, v6, v8
	s_waitcnt lgkmcnt(3)
	s_waitcnt lgkmcnt(2)
	ds_read2_b32 v[18:19], v1 offset0:214 offset1:222
	ds_read2_b32 v[20:21], v1 offset0:247 offset1:255
	v_cvt_pk_bf16_f32 v3, v10, v12
	s_waitcnt lgkmcnt(3)
	s_waitcnt lgkmcnt(2)
	v_cvt_pk_bf16_f32 v4, v14, v16
	s_waitcnt lgkmcnt(1)
	s_waitcnt lgkmcnt(0)
	v_cvt_pk_bf16_f32 v5, v18, v20
	buffer_store_dwordx4 v[2:5], v72, s[4:7], 0 offen sc1
	s_nop 1
	v_cvt_pk_bf16_f32 v2, v7, v9
	v_cvt_pk_bf16_f32 v3, v11, v13
	v_cvt_pk_bf16_f32 v4, v15, v17
	v_cvt_pk_bf16_f32 v5, v19, v21
	buffer_store_dwordx4 v[2:5], v73, s[4:7], 0 offen sc1
	s_nop 1
	s_waitcnt lgkmcnt(0)
	s_cmp_eq_u32 s57, 16
	s_cbranch_scc1 .LBB0_119
	s_waitcnt vmcnt(12)
	s_barrier
	s_and_saveexec_b64 s[4:5], s[2:3]
	s_cbranch_execz .LBB0_118
	s_mov_b64 s[38:39], exec
	v_mbcnt_lo_u32_b32 v2, s38, 0
	v_mbcnt_hi_u32_b32 v2, s39, v2
	v_cmp_eq_u32_e32 vcc, 0, v2
	s_and_b64 s[40:41], exec, vcc
	s_mov_b64 exec, s[40:41]
	s_cbranch_execz .LBB0_118
	s_bcnt1_i32_b64 s28, s[38:39]
	v_mov_b32_e32 v2, s28
	global_atomic_add v67, v2, s[30:31]

; #define LAS __attribute__((address_space(3)))
; #define LDS_WAIT() asm volatile("s_waitcnt lgkmcnt(0)" ::: "memory")
; __device__ __forceinline__ unsigned pk2(float lo, float hi) { return (unsigned)f2bf(lo) | ((unsigned)f2bf(hi) << 16); }
; __device__ __forceinline__ unsigned xb_add(unsigned* p, unsigned v) { return __hip_atomic_fetch_add(p, v, __ATOMIC_RELAXED, __HIP_MEMORY_SCOPE_AGENT); }
; __device__ __forceinline__ void p0_item_load(const P0Item& d, f32x4 (&v)[8], int lane) {
; #pragma unroll
;     for (int i = 0; i < 8; ++i) v[i] = __builtin_nontemporal_load((const f32x4*)(d.src + (size_t)(8 * i + (lane >> 3)) * d.N + 4 * (lane & 7)));
; }
; template <bool WT = false>
; __device__ __forceinline__ void p0_item_finish(const P0Item& d, const f32x4 (&v)[8], LAS float* scr, int lane) {
; #pragma unroll
;     for (int i = 0; i < 8; ++i) { LAS float* q = scr + (8 * i + (lane >> 3)) * 33 + 4 * (lane & 7); q[0] = v[i][0]; q[1] = v[i][1]; q[2] = v[i][2]; q[3] = v[i][3]; }
;     LDS_WAIT(); asm volatile("" ::: "memory");
;     const int c = lane & 7;
; #pragma unroll
;     for (int j = 0; j < 4; ++j) { const int n = (lane >> 3) + 8 * j; const LAS float* s = scr + (8 * c) * 33 + n;
;         v4u o; o.x = pk2(s[0 * 33], s[1 * 33]); o.y = pk2(s[2 * 33], s[3 * 33]); o.z = pk2(s[4 * 33], s[5 * 33]); o.w = pk2(s[6 * 33], s[7 * 33]);
;         if constexpr (WT) __builtin_amdgcn_raw_buffer_store_b128(o, __builtin_amdgcn_make_buffer_rsrc((void*)d.dst, 0, 0x7fffffff, 0x00020000), (int)(((size_t)n * d.ldt + 8 * c) * 2), 0, 16);
;         else *(v4u*)(d.dst + (size_t)n * d.ldt + 8 * c) = o; }
;     LDS_WAIT(); asm volatile("" ::: "memory");
; }
; __device__ __forceinline__ void tr_blocks(Frame& F, const Args& a, int T, int b_lo, int b_hi, bool tail) {
;     ...
;         da = p0_item_in(a, T, b + 2 < b_hi ? 8 * (b + 2) + w : (tail ? 448 : 8 * b + w)); p0_item_load(da, va, F.lane);
;         p0_item_finish<true>(db, vb, scr, F.lane);
;         asm volatile("s_waitcnt vmcnt(12)" ::: "memory"); __syncthreads(); if (F.tid == 0) (void)xb_add(blk + 16 * b, 1u);
.LBB0_124:
	s_ashr_i32 s5, s4, 31
	v_lshl_add_u64 v[2:3], s[4:5], 2, v[68:69]
	v_lshl_add_u64 v[26:27], v[2:3], 0, v[66:67]
	v_add_co_u32_e32 v6, vcc, 0x70000, v26
	s_and_b32 s5, s55, 0xffff
	s_nop 0
	v_addc_co_u32_e32 v7, vcc, 0, v27, vcc
	v_add_co_u32_e32 v10, vcc, 0xe0000, v26
	global_load_dwordx4 v[2:5], v[26:27], off nt
	s_nop 0
	global_load_dwordx4 v[6:9], v[6:7], off offset:1024 nt
	v_addc_co_u32_e32 v11, vcc, 0, v27, vcc
	v_add_co_u32_e32 v14, vcc, 0x150000, v26
	s_mov_b32 s4, s54
	s_nop 0
	v_addc_co_u32_e32 v15, vcc, 0, v27, vcc
	v_add_co_u32_e32 v18, vcc, 0x1c1000, v26
	global_load_dwordx4 v[10:13], v[10:11], off offset:2048 nt
	s_nop 0
	global_load_dwordx4 v[14:17], v[14:15], off offset:3072 nt
	v_addc_co_u32_e32 v19, vcc, 0, v27, vcc
	v_add_co_u32_e32 v22, vcc, 0x231000, v26
	s_nop 1
	v_addc_co_u32_e32 v23, vcc, 0, v27, vcc
	v_add_co_u32_e32 v28, vcc, 0x2a1000, v26
	global_load_dwordx4 v[18:21], v[18:19], off nt
	s_nop 0
	global_load_dwordx4 v[22:25], v[22:23], off offset:1024 nt
	v_addc_co_u32_e32 v29, vcc, 0, v27, vcc
	v_add_co_u32_e32 v30, vcc, 0x311000, v26
	s_nop 1
	v_addc_co_u32_e32 v31, vcc, 0, v27, vcc
	global_load_dwordx4 v[26:29], v[28:29], off offset:2048 nt
	s_nop 0
	global_load_dwordx4 v[30:33], v[30:31], off offset:3072 nt
	s_waitcnt vmcnt(19)
	ds_write2_b32 v74, v34, v35 offset1:1
	ds_write2_b32 v74, v36, v37 offset0:2 offset1:3
	s_waitcnt vmcnt(18)
	ds_write2_b32 v75, v38, v39 offset1:1
	ds_write2_b32 v76, v40, v41 offset1:1
	s_waitcnt vmcnt(17)
	ds_write2_b32 v77, v42, v43 offset1:1
	ds_write2_b32 v78, v44, v45 offset1:1
	s_waitcnt vmcnt(16)
	ds_write2_b32 v79, v46, v47 offset1:1
	ds_write2_b32 v80, v48, v49 offset1:1
	s_waitcnt vmcnt(15)
	ds_write2_b32 v81, v50, v51 offset1:1
	ds_write2_b32 v82, v52, v53 offset1:1
	s_waitcnt vmcnt(14)
	ds_write2_b32 v83, v54, v55 offset1:1
	ds_write2_b32 v84, v56, v57 offset1:1
	s_waitcnt vmcnt(13)
	ds_write2_b32 v85, v58, v59 offset1:1
	ds_write2_b32 v86, v60, v61 offset1:1
	s_waitcnt vmcnt(12)
	ds_write2_b32 v87, v62, v63 offset1:1
	ds_write2_b32 v88, v64, v65 offset1:1
	s_waitcnt lgkmcnt(0)
	ds_read2_b32 v[38:39], v1 offset1:8
	ds_read2_b32 v[40:41], v1 offset0:33 offset1:41
	ds_read2_b32 v[42:43], v1 offset0:66 offset1:74
	ds_read2_b32 v[44:45], v1 offset0:99 offset1:107
	ds_read2_b32 v[46:47], v1 offset0:132 offset1:140
	s_waitcnt lgkmcnt(4)
	s_waitcnt lgkmcnt(3)
	ds_read2_b32 v[48:49], v1 offset0:165 offset1:173
	v_cvt_pk_bf16_f32 v34, v38, v40
	s_waitcnt lgkmcnt(3)
	s_waitcnt lgkmcnt(2)
	ds_read2_b32 v[50:51], v1 offset0:198 offset1:206
	ds_read2_b32 v[52:53], v1 offset0:231 offset1:239
	v_cvt_pk_bf16_f32 v35, v42, v44
	s_waitcnt lgkmcnt(3)
	s_waitcnt lgkmcnt(2)
	v_cvt_pk_bf16_f32 v36, v46, v48
	s_waitcnt lgkmcnt(1)
	s_waitcnt lgkmcnt(0)
	v_cvt_pk_bf16_f32 v37, v50, v52
	buffer_store_dwordx4 v[34:37], v70, s[4:7], 0 offen sc1
	s_nop 1
	v_cvt_pk_bf16_f32 v34, v39, v41
	v_cvt_pk_bf16_f32 v35, v43, v45
	v_cvt_pk_bf16_f32 v36, v47, v49
	ds_read2_b32 v[38:39], v1 offset0:16 offset1:24
	v_cvt_pk_bf16_f32 v37, v51, v53
	ds_read2_b32 v[40:41], v1 offset0:49 offset1:57
	ds_read2_b32 v[42:43], v1 offset0:82 offset1:90
	ds_read2_b32 v[44:45], v1 offset0:115 offset1:123
	buffer_store_dwordx4 v[34:37], v71, s[4:7], 0 offen sc1
	s_nop 1
	ds_read2_b32 v[46:47], v1 offset0:148 offset1:156
	ds_read2_b32 v[48:49], v1 offset0:181 offset1:189
	s_waitcnt lgkmcnt(5)
	s_waitcnt lgkmcnt(4)
	v_cvt_pk_bf16_f32 v34, v38, v40
	s_waitcnt lgkmcnt(3)
	s_waitcnt lgkmcnt(2)
	ds_read2_b32 v[50:51], v1 offset0:214 offset1:222
	ds_read2_b32 v[52:53], v1 offset0:247 offset1:255
	v_cvt_pk_bf16_f32 v35, v42, v44
	s_waitcnt lgkmcnt(3)
	s_waitcnt lgkmcnt(2)
	v_cvt_pk_bf16_f32 v36, v46, v48
	s_waitcnt lgkmcnt(1)
	s_waitcnt lgkmcnt(0)
	v_cvt_pk_bf16_f32 v37, v50, v52
	buffer_store_dwordx4 v[34:37], v72, s[4:7], 0 offen sc1
	s_nop 1
	v_cvt_pk_bf16_f32 v34, v39, v41
	v_cvt_pk_bf16_f32 v35, v43, v45
	v_cvt_pk_bf16_f32 v36, v47, v49
	v_cvt_pk_bf16_f32 v37, v51, v53
	buffer_store_dwordx4 v[34:37], v73, s[4:7], 0 offen sc1
	s_nop 1
	s_waitcnt lgkmcnt(0)
	s_waitcnt vmcnt(12)
	s_barrier
	s_and_saveexec_b64 s[4:5], s[2:3]
	s_cbranch_execz .LBB0_108
	s_mov_b64 s[40:41], exec
	v_mbcnt_lo_u32_b32 v34, s40, 0
	v_mbcnt_hi_u32_b32 v34, s41, v34
	v_cmp_eq_u32_e32 vcc, 0, v34
	s_and_b64 s[62:63], exec, vcc
	s_mov_b64 exec, s[62:63]
	s_cbranch_execz .LBB0_108
	s_bcnt1_i32_b64 s40, s[40:41]
	v_mov_b32_e32 v34, s40
	global_atomic_add v67, v34, s[30:31] offset:64
	s_branch .LBB0_108

; #define LAS __attribute__((address_space(3)))
; #define LDS_WAIT() asm volatile("s_waitcnt lgkmcnt(0)" ::: "memory")
; __device__ __forceinline__ unsigned pk2(float lo, float hi) { return (unsigned)f2bf(lo) | ((unsigned)f2bf(hi) << 16); }
; __device__ __forceinline__ unsigned xb_add(unsigned* p, unsigned v) { return __hip_atomic_fetch_add(p, v, __ATOMIC_RELAXED, __HIP_MEMORY_SCOPE_AGENT); }
; __device__ __forceinline__ void p0_item_load(const P0Item& d, f32x4 (&v)[8], int lane) {
; #pragma unroll
;     for (int i = 0; i < 8; ++i) v[i] = __builtin_nontemporal_load((const f32x4*)(d.src + (size_t)(8 * i + (lane >> 3)) * d.N + 4 * (lane & 7)));
; }
; template <bool WT = false>
; __device__ __forceinline__ void p0_item_finish(const P0Item& d, const f32x4 (&v)[8], LAS float* scr, int lane) {
; #pragma unroll
;     for (int i = 0; i < 8; ++i) { LAS float* q = scr + (8 * i + (lane >> 3)) * 33 + 4 * (lane & 7); q[0] = v[i][0]; q[1] = v[i][1]; q[2] = v[i][2]; q[3] = v[i][3]; }
;     LDS_WAIT(); asm volatile("" ::: "memory");
;     const int c = lane & 7;
; #pragma unroll
;     for (int j = 0; j < 4; ++j) { const int n = (lane >> 3) + 8 * j; const LAS float* s = scr + (8 * c) * 33 + n;
;         v4u o; o.x = pk2(s[0 * 33], s[1 * 33]); o.y = pk2(s[2 * 33], s[3 * 33]); o.z = pk2(s[4 * 33], s[5 * 33]); o.w = pk2(s[6 * 33], s[7 * 33]);
;         if constexpr (WT) __builtin_amdgcn_raw_buffer_store_b128(o, __builtin_amdgcn_make_buffer_rsrc((void*)d.dst, 0, 0x7fffffff, 0x00020000), (int)(((size_t)n * d.ldt + 8 * c) * 2), 0, 16);
;         else *(v4u*)(d.dst + (size_t)n * d.ldt + 8 * c) = o; }
;     LDS_WAIT(); asm volatile("" ::: "memory");
; }
; __device__ __forceinline__ void tr_blocks(Frame& F, const Args& a, int T, int b_lo, int b_hi, bool tail) {
;     ...
;         db = p0_item_in(a, T, 8 * (b + 1) + w); p0_item_load(db, vb, F.lane);
;         p0_item_finish<true>(da, va, scr, F.lane);
;         if (b > b_lo) { asm volatile("s_waitcnt vmcnt(12)" ::: "memory"); __syncthreads(); if (F.tid == 0) (void)xb_add(blk + 16 * (b - 1), 1u); }
.LBB0_394:
	s_ashr_i32 s39, s38, 31
	s_lshl_b64 s[38:39], s[38:39], 2
	s_add_u32 s38, s0, s38
	s_addc_u32 s39, s1, s39
	v_lshl_add_u64 v[34:35], s[38:39], 0, v[70:71]
	v_lshl_add_u64 v[36:37], s[38:39], 0, v[72:73]
	v_lshl_add_u64 v[42:43], s[38:39], 0, v[74:75]
	v_lshl_add_u64 v[44:45], s[38:39], 0, v[76:77]
	v_lshl_add_u64 v[50:51], s[38:39], 0, v[78:79]
	v_lshl_add_u64 v[52:53], s[38:39], 0, v[80:81]
	v_lshl_add_u64 v[58:59], s[38:39], 0, v[82:83]
	v_lshl_add_u64 v[60:61], s[38:39], 0, v[84:85]
	v_lshl_add_u64 v[34:35], v[34:35], 0, v[66:67]
	v_lshl_add_u64 v[36:37], v[36:37], 0, v[66:67]
	v_lshl_add_u64 v[42:43], v[42:43], 0, v[66:67]
	v_lshl_add_u64 v[44:45], v[44:45], 0, v[66:67]
	v_lshl_add_u64 v[50:51], v[50:51], 0, v[66:67]
	v_lshl_add_u64 v[52:53], v[52:53], 0, v[66:67]
	v_lshl_add_u64 v[58:59], v[58:59], 0, v[66:67]
	v_lshl_add_u64 v[60:61], v[60:61], 0, v[66:67]
	global_load_dwordx4 v[38:41], v[34:35], off nt
	s_nop 0
	global_load_dwordx4 v[34:37], v[36:37], off nt
	s_nop 0
	global_load_dwordx4 v[46:49], v[42:43], off nt
	s_nop 0
	global_load_dwordx4 v[42:45], v[44:45], off nt
	s_nop 0
	global_load_dwordx4 v[54:57], v[50:51], off nt
	s_nop 0
	global_load_dwordx4 v[50:53], v[52:53], off nt
	s_nop 0
	global_load_dwordx4 v[62:65], v[58:59], off nt
	s_nop 0
	global_load_dwordx4 v[58:61], v[60:61], off nt
	v_add_u32_e32 v98, 0x420, v93
	v_add_u32_e32 v99, 0x428, v93
	v_add_u32_e32 v100, 0x840, v93
	v_add_u32_e32 v101, 0x848, v93
	v_add_u32_e32 v102, 0xc60, v93
	v_add_u32_e32 v103, 0xc68, v93
	v_add_u32_e32 v104, 0x1080, v93
	v_add_u32_e32 v105, 0x1088, v93
	v_add_u32_e32 v106, 0x14a0, v93
	v_add_u32_e32 v107, 0x14a8, v93
	v_add_u32_e32 v108, 0x18c0, v93
	v_add_u32_e32 v109, 0x18c8, v93
	v_add_u32_e32 v110, 0x1ce0, v93
	v_add_u32_e32 v111, 0x1ce8, v93
	s_waitcnt vmcnt(15)
	ds_write2_b32 v93, v6, v7 offset1:1
	ds_write2_b32 v93, v8, v9 offset0:2 offset1:3
	s_waitcnt vmcnt(14)
	ds_write2_b32 v98, v2, v3 offset1:1
	ds_write2_b32 v99, v4, v5 offset1:1
	s_waitcnt vmcnt(13)
	ds_write2_b32 v100, v14, v15 offset1:1
	ds_write2_b32 v101, v16, v17 offset1:1
	s_waitcnt vmcnt(12)
	ds_write2_b32 v102, v10, v11 offset1:1
	ds_write2_b32 v103, v12, v13 offset1:1
	s_waitcnt vmcnt(11)
	ds_write2_b32 v104, v22, v23 offset1:1
	ds_write2_b32 v105, v24, v25 offset1:1
	s_waitcnt vmcnt(10)
	ds_write2_b32 v106, v18, v19 offset1:1
	ds_write2_b32 v107, v20, v21 offset1:1
	s_waitcnt vmcnt(9)
	ds_write2_b32 v108, v30, v31 offset1:1
	ds_write2_b32 v109, v32, v33 offset1:1
	s_waitcnt vmcnt(8)
	ds_write2_b32 v110, v26, v27 offset1:1
	ds_write2_b32 v111, v28, v29 offset1:1
	s_waitcnt lgkmcnt(0)
	ds_read2_b32 v[6:7], v92 offset1:8
	ds_read2_b32 v[8:9], v92 offset0:33 offset1:41
	ds_read2_b32 v[10:11], v92 offset0:66 offset1:74
	ds_read2_b32 v[12:13], v92 offset0:99 offset1:107
	ds_read2_b32 v[14:15], v92 offset0:132 offset1:140
	s_waitcnt lgkmcnt(4)
	s_waitcnt lgkmcnt(3)
	ds_read2_b32 v[16:17], v92 offset0:165 offset1:173
	v_cvt_pk_bf16_f32 v2, v6, v8
	s_waitcnt lgkmcnt(3)
	s_waitcnt lgkmcnt(2)
	ds_read2_b32 v[18:19], v92 offset0:198 offset1:206
	ds_read2_b32 v[20:21], v92 offset0:231 offset1:239
	v_cvt_pk_bf16_f32 v3, v10, v12
	s_waitcnt lgkmcnt(3)
	s_waitcnt lgkmcnt(2)
	v_cvt_pk_bf16_f32 v4, v14, v16
	s_waitcnt lgkmcnt(1)
	s_waitcnt lgkmcnt(0)
	s_and_b32 s5, s5, 0xffff
	v_cvt_pk_bf16_f32 v5, v18, v20
	buffer_store_dwordx4 v[2:5], v97, s[4:7], 0 offen sc1
	s_nop 1
	v_cvt_pk_bf16_f32 v2, v7, v9
	v_cvt_pk_bf16_f32 v3, v11, v13
	v_cvt_pk_bf16_f32 v4, v15, v17
	ds_read2_b32 v[6:7], v92 offset0:16 offset1:24
	v_cvt_pk_bf16_f32 v5, v19, v21
	ds_read2_b32 v[8:9], v92 offset0:49 offset1:57
	ds_read2_b32 v[10:11], v92 offset0:82 offset1:90
	ds_read2_b32 v[12:13], v92 offset0:115 offset1:123
	buffer_store_dwordx4 v[2:5], v96, s[4:7], 0 offen sc1
	s_nop 1
	ds_read2_b32 v[14:15], v92 offset0:148 offset1:156
	ds_read2_b32 v[16:17], v92 offset0:181 offset1:189
	s_waitcnt lgkmcnt(5)
	s_waitcnt lgkmcnt(4)
	v_cvt_pk_bf16_f32 v2, v6, v8
	s_waitcnt lgkmcnt(3)
	s_waitcnt lgkmcnt(2)
	ds_read2_b32 v[18:19], v92 offset0:214 offset1:222
	ds_read2_b32 v[20:21], v92 offset0:247 offset1:255
	v_cvt_pk_bf16_f32 v3, v10, v12
	s_waitcnt lgkmcnt(3)
	s_waitcnt lgkmcnt(2)
	v_cvt_pk_bf16_f32 v4, v14, v16
	s_waitcnt lgkmcnt(1)
	s_waitcnt lgkmcnt(0)
	v_cvt_pk_bf16_f32 v5, v18, v20
	buffer_store_dwordx4 v[2:5], v95, s[4:7], 0 offen sc1
	s_nop 1
	v_cvt_pk_bf16_f32 v2, v7, v9
	v_cvt_pk_bf16_f32 v3, v11, v13
	v_cvt_pk_bf16_f32 v4, v15, v17
	v_cvt_pk_bf16_f32 v5, v19, v21
	buffer_store_dwordx4 v[2:5], v94, s[4:7], 0 offen sc1
	s_nop 1
	s_waitcnt lgkmcnt(0)
	s_cmp_lt_u32 s10, 9
	s_cbranch_scc1 .LBB0_399
	s_waitcnt vmcnt(12)
	s_barrier
	s_and_saveexec_b64 s[4:5], s[2:3]
	s_cbranch_execz .LBB0_398
	s_mov_b64 s[38:39], exec
	v_mbcnt_lo_u32_b32 v2, s38, 0
	v_mbcnt_hi_u32_b32 v2, s39, v2
	v_cmp_eq_u32_e32 vcc, 0, v2
	s_and_b64 s[40:41], exec, vcc
	s_mov_b64 exec, s[40:41]
	s_cbranch_execz .LBB0_398
	s_bcnt1_i32_b64 s28, s[38:39]
	v_mov_b32_e32 v2, s28
	global_atomic_add v67, v2, s[30:31]

; #define LAS __attribute__((address_space(3)))
; #define LDS_WAIT() asm volatile("s_waitcnt lgkmcnt(0)" ::: "memory")
; __device__ __forceinline__ unsigned pk2(float lo, float hi) { return (unsigned)f2bf(lo) | ((unsigned)f2bf(hi) << 16); }
; __device__ __forceinline__ unsigned xb_add(unsigned* p, unsigned v) { return __hip_atomic_fetch_add(p, v, __ATOMIC_RELAXED, __HIP_MEMORY_SCOPE_AGENT); }
; __device__ __forceinline__ void p0_item_load(const P0Item& d, f32x4 (&v)[8], int lane) {
; #pragma unroll
;     for (int i = 0; i < 8; ++i) v[i] = __builtin_nontemporal_load((const f32x4*)(d.src + (size_t)(8 * i + (lane >> 3)) * d.N + 4 * (lane & 7)));
; }
; template <bool WT = false>
; __device__ __forceinline__ void p0_item_finish(const P0Item& d, const f32x4 (&v)[8], LAS float* scr, int lane) {
; #pragma unroll
;     for (int i = 0; i < 8; ++i) { LAS float* q = scr + (8 * i + (lane >> 3)) * 33 + 4 * (lane & 7); q[0] = v[i][0]; q[1] = v[i][1]; q[2] = v[i][2]; q[3] = v[i][3]; }
;     LDS_WAIT(); asm volatile("" ::: "memory");
;     const int c = lane & 7;
; #pragma unroll
;     for (int j = 0; j < 4; ++j) { const int n = (lane >> 3) + 8 * j; const LAS float* s = scr + (8 * c) * 33 + n;
;         v4u o; o.x = pk2(s[0 * 33], s[1 * 33]); o.y = pk2(s[2 * 33], s[3 * 33]); o.z = pk2(s[4 * 33], s[5 * 33]); o.w = pk2(s[6 * 33], s[7 * 33]);
;         if constexpr (WT) __builtin_amdgcn_raw_buffer_store_b128(o, __builtin_amdgcn_make_buffer_rsrc((void*)d.dst, 0, 0x7fffffff, 0x00020000), (int)(((size_t)n * d.ldt + 8 * c) * 2), 0, 16);
;         else *(v4u*)(d.dst + (size_t)n * d.ldt + 8 * c) = o; }
;     LDS_WAIT(); asm volatile("" ::: "memory");
; }
; __device__ __forceinline__ void tr_blocks(Frame& F, const Args& a, int T, int b_lo, int b_hi, bool tail) {
;     ...
;         da = p0_item_in(a, T, b + 2 < b_hi ? 8 * (b + 2) + w : (tail ? 448 : 8 * b + w)); p0_item_load(da, va, F.lane);
;         p0_item_finish<true>(db, vb, scr, F.lane);
;         asm volatile("s_waitcnt vmcnt(12)" ::: "memory"); __syncthreads(); if (F.tid == 0) (void)xb_add(blk + 16 * b, 1u);
.LBB0_404:
	s_ashr_i32 s5, s4, 31
	s_lshl_b64 s[4:5], s[4:5], 2
	s_add_u32 s4, s0, s4
	s_addc_u32 s5, s1, s5
	v_lshl_add_u64 v[2:3], s[4:5], 0, v[70:71]
	v_lshl_add_u64 v[4:5], s[4:5], 0, v[72:73]
	v_lshl_add_u64 v[10:11], s[4:5], 0, v[74:75]
	v_lshl_add_u64 v[12:13], s[4:5], 0, v[76:77]
	v_lshl_add_u64 v[18:19], s[4:5], 0, v[78:79]
	v_lshl_add_u64 v[20:21], s[4:5], 0, v[80:81]
	v_lshl_add_u64 v[26:27], s[4:5], 0, v[82:83]
	v_lshl_add_u64 v[28:29], s[4:5], 0, v[84:85]
	v_lshl_add_u64 v[2:3], v[2:3], 0, v[66:67]
	v_lshl_add_u64 v[4:5], v[4:5], 0, v[66:67]
	v_lshl_add_u64 v[10:11], v[10:11], 0, v[66:67]
	v_lshl_add_u64 v[12:13], v[12:13], 0, v[66:67]
	v_lshl_add_u64 v[18:19], v[18:19], 0, v[66:67]
	v_lshl_add_u64 v[20:21], v[20:21], 0, v[66:67]
	v_lshl_add_u64 v[26:27], v[26:27], 0, v[66:67]
	v_lshl_add_u64 v[28:29], v[28:29], 0, v[66:67]
	global_load_dwordx4 v[6:9], v[2:3], off nt
	s_nop 0
	global_load_dwordx4 v[2:5], v[4:5], off nt
	s_nop 0
	global_load_dwordx4 v[14:17], v[10:11], off nt
	s_nop 0
	global_load_dwordx4 v[10:13], v[12:13], off nt
	s_nop 0
	global_load_dwordx4 v[22:25], v[18:19], off nt
	s_nop 0
	global_load_dwordx4 v[18:21], v[20:21], off nt
	s_nop 0
	global_load_dwordx4 v[30:33], v[26:27], off nt
	s_nop 0
	global_load_dwordx4 v[26:29], v[28:29], off nt
	s_waitcnt vmcnt(19)
	ds_write2_b32 v93, v38, v39 offset1:1
	ds_write2_b32 v93, v40, v41 offset0:2 offset1:3
	s_waitcnt vmcnt(18)
	ds_write2_b32 v98, v34, v35 offset1:1
	ds_write2_b32 v99, v36, v37 offset1:1
	s_waitcnt vmcnt(17)
	ds_write2_b32 v100, v46, v47 offset1:1
	ds_write2_b32 v101, v48, v49 offset1:1
	s_waitcnt vmcnt(16)
	ds_write2_b32 v102, v42, v43 offset1:1
	ds_write2_b32 v103, v44, v45 offset1:1
	s_waitcnt vmcnt(15)
	ds_write2_b32 v104, v54, v55 offset1:1
	ds_write2_b32 v105, v56, v57 offset1:1
	s_waitcnt vmcnt(14)
	ds_write2_b32 v106, v50, v51 offset1:1
	ds_write2_b32 v107, v52, v53 offset1:1
	s_waitcnt vmcnt(13)
	ds_write2_b32 v108, v62, v63 offset1:1
	ds_write2_b32 v109, v64, v65 offset1:1
	s_waitcnt vmcnt(12)
	ds_write2_b32 v110, v58, v59 offset1:1
	ds_write2_b32 v111, v60, v61 offset1:1
	s_waitcnt lgkmcnt(0)
	ds_read2_b32 v[38:39], v92 offset1:8
	ds_read2_b32 v[40:41], v92 offset0:33 offset1:41
	ds_read2_b32 v[42:43], v92 offset0:66 offset1:74
	ds_read2_b32 v[44:45], v92 offset0:99 offset1:107
	ds_read2_b32 v[46:47], v92 offset0:132 offset1:140
	s_waitcnt lgkmcnt(4)
	s_waitcnt lgkmcnt(3)
	ds_read2_b32 v[48:49], v92 offset0:165 offset1:173
	v_cvt_pk_bf16_f32 v34, v38, v40
	s_waitcnt lgkmcnt(3)
	s_waitcnt lgkmcnt(2)
	ds_read2_b32 v[50:51], v92 offset0:198 offset1:206
	ds_read2_b32 v[52:53], v92 offset0:231 offset1:239
	v_cvt_pk_bf16_f32 v35, v42, v44
	s_waitcnt lgkmcnt(3)
	s_waitcnt lgkmcnt(2)
	v_cvt_pk_bf16_f32 v36, v46, v48
	s_waitcnt lgkmcnt(1)
	s_waitcnt lgkmcnt(0)
	s_and_b32 s5, s54, 0xffff
	s_mov_b32 s4, s53
	v_cvt_pk_bf16_f32 v37, v50, v52
	buffer_store_dwordx4 v[34:37], v97, s[4:7], 0 offen sc1
	s_nop 1
	v_cvt_pk_bf16_f32 v34, v39, v41
	v_cvt_pk_bf16_f32 v35, v43, v45
	v_cvt_pk_bf16_f32 v36, v47, v49
	ds_read2_b32 v[38:39], v92 offset0:16 offset1:24
	v_cvt_pk_bf16_f32 v37, v51, v53
	ds_read2_b32 v[40:41], v92 offset0:49 offset1:57
	ds_read2_b32 v[42:43], v92 offset0:82 offset1:90
	ds_read2_b32 v[44:45], v92 offset0:115 offset1:123
	buffer_store_dwordx4 v[34:37], v96, s[4:7], 0 offen sc1
	s_nop 1
	ds_read2_b32 v[46:47], v92 offset0:148 offset1:156
	ds_read2_b32 v[48:49], v92 offset0:181 offset1:189
	s_waitcnt lgkmcnt(5)
	s_waitcnt lgkmcnt(4)
	v_cvt_pk_bf16_f32 v34, v38, v40
	s_waitcnt lgkmcnt(3)
	s_waitcnt lgkmcnt(2)
	ds_read2_b32 v[50:51], v92 offset0:214 offset1:222
	ds_read2_b32 v[52:53], v92 offset0:247 offset1:255
	v_cvt_pk_bf16_f32 v35, v42, v44
	s_waitcnt lgkmcnt(3)
	s_waitcnt lgkmcnt(2)
	v_cvt_pk_bf16_f32 v36, v46, v48
	s_waitcnt lgkmcnt(1)
	s_waitcnt lgkmcnt(0)
	v_cvt_pk_bf16_f32 v37, v50, v52
	buffer_store_dwordx4 v[34:37], v95, s[4:7], 0 offen sc1
	s_nop 1
	v_cvt_pk_bf16_f32 v34, v39, v41
	v_cvt_pk_bf16_f32 v35, v43, v45
	v_cvt_pk_bf16_f32 v36, v47, v49
	v_cvt_pk_bf16_f32 v37, v51, v53
	buffer_store_dwordx4 v[34:37], v94, s[4:7], 0 offen sc1
	s_nop 1
	s_waitcnt lgkmcnt(0)
	s_waitcnt vmcnt(12)
	s_barrier
	s_and_saveexec_b64 s[4:5], s[2:3]
	s_cbranch_execz .LBB0_388
	s_mov_b64 s[40:41], exec
	v_mbcnt_lo_u32_b32 v34, s40, 0
	v_mbcnt_hi_u32_b32 v34, s41, v34
	v_cmp_eq_u32_e32 vcc, 0, v34
	s_and_b64 s[58:59], exec, vcc
	s_mov_b64 exec, s[58:59]
	s_cbranch_execz .LBB0_388
	s_bcnt1_i32_b64 s40, s[40:41]
	v_mov_b32_e32 v34, s40
	global_atomic_add v67, v34, s[30:31] offset:64
	s_branch .LBB0_388
